# lnmix: next tile's first row prefetched into spare VGPRs during the current tile
# baseline (speedup 1.0000x reference)
.LBB0_748:
	s_or_b64 exec, exec, s[0:1]
	s_cmpk_gt_i32 s2, 0x3ff
	s_cbranch_scc1 .LBB0_755
	v_readlane_b32 s8, v126, 2
	v_readlane_b32 s9, v126, 3
	v_readlane_b32 s10, v126, 4
	v_readlane_b32 s11, v126, 5
	v_readlane_b32 s12, v126, 6
	v_readlane_b32 s13, v126, 7
	s_waitcnt vmcnt(14)
	v_and_b32_e32 v6, 63, v2
	v_readlane_b32 s14, v126, 8
	v_readlane_b32 s15, v126, 9
	s_mov_b64 s[8:9], s[12:13]
	v_mov_b32_e32 v1, 0
	s_mov_b64 s[10:11], s[14:15]
	v_lshlrev_b32_e32 v4, 3, v6
	v_mov_b32_e32 v5, v1
	v_mbcnt_lo_u32_b32 v3, -1, 0
	v_lshl_add_u64 v[4:5], s[10:11], 0, v[4:5]
	s_mov_b64 s[0:1], 0x1d3e8000
	v_mbcnt_hi_u32_b32 v3, -1, v3
	v_lshl_add_u64 v[8:9], v[4:5], 0, s[0:1]
	v_and_b32_e32 v4, 64, v3
	v_add_u32_e32 v4, 64, v4
	v_xor_b32_e32 v5, 1, v3
	v_cmp_lt_i32_e32 vcc, v5, v4
	s_add_u32 s12, s10, 0x18e80000
	v_ashrrev_i32_e32 v7, 6, v2
	v_cndmask_b32_e32 v5, v3, v5, vcc
	s_waitcnt vmcnt(5)
	v_lshlrev_b32_e32 v45, 2, v5
	v_xor_b32_e32 v5, 2, v3
	v_cmp_lt_i32_e32 vcc, v5, v4
	s_addc_u32 s13, s11, 0
	v_and_b32_e32 v19, 15, v2
	v_cndmask_b32_e32 v5, v3, v5, vcc
	s_waitcnt vmcnt(4)
	v_lshlrev_b32_e32 v46, 2, v5
	v_xor_b32_e32 v5, 4, v3
	v_cmp_lt_i32_e32 vcc, v5, v4
	v_bfe_u32 v21, v2, 4, 2
	s_add_i32 s0, 0, 0x20100
	v_cndmask_b32_e32 v5, v3, v5, vcc
	v_lshlrev_b32_e32 v47, 2, v5
	v_xor_b32_e32 v5, 8, v3
	v_cmp_lt_i32_e32 vcc, v5, v4
	s_movk_i32 s1, 0x100
	v_lshlrev_b32_e32 v44, 1, v7
	v_cndmask_b32_e32 v5, v3, v5, vcc
	v_lshlrev_b32_e32 v48, 2, v5
	v_xor_b32_e32 v5, 16, v3
	v_cmp_lt_i32_e32 vcc, v5, v4
	v_cmp_gt_i32_e64 s[4:5], s1, v2
	s_waitcnt vmcnt(3)
	v_lshl_add_u32 v52, v2, 2, s0
	v_cndmask_b32_e32 v5, v3, v5, vcc
	v_lshlrev_b32_e32 v49, 2, v5
	v_xor_b32_e32 v5, 32, v3
	v_cmp_lt_i32_e32 vcc, v5, v4
	v_lshlrev_b32_e32 v4, 2, v19
	v_ashrrev_i32_e32 v53, 4, v2
	v_cndmask_b32_e32 v3, v3, v5, vcc
	v_lshlrev_b32_e32 v50, 2, v3
	v_lshl_add_u32 v3, v7, 10, s0
	v_lshlrev_b32_e32 v5, 8, v21
	v_add3_u32 v51, v3, v5, v4
	v_mov_b32_e32 v5, v1
	v_lshl_add_u64 v[2:3], s[10:11], 0, v[4:5]
	s_mov_b64 s[0:1], 0x18fc8000
	v_lshl_add_u64 v[10:11], v[2:3], 0, s[0:1]
	s_movk_i32 s0, 0x2020
	v_lshlrev_b32_e32 v2, 4, v6
	v_mov_b32_e32 v3, v1
	s_waitcnt vmcnt(2)
	v_or_b32_e32 v55, 1, v44
	s_movk_i32 s8, 0x1010
	v_lshlrev_b32_e32 v0, 2, v6
	v_mul_lo_u32 v5, v7, s0
	s_add_i32 s0, 0, 0x10000
	v_lshl_add_u64 v[12:13], s[50:51], 0, v[2:3]
	v_lshl_add_u64 v[14:15], s[52:53], 0, v[2:3]
	v_mul_lo_u32 v3, v55, s8
	v_add3_u32 v54, s0, v5, v2
	v_add3_u32 v56, s0, v3, v2
	v_lshl_add_u64 v[2:3], s[10:11], 0, v[0:1]
	s_mov_b64 s[0:1], 0x1b3e8000
	v_lshl_add_u64 v[16:17], v[2:3], 0, s[0:1]
	v_lshlrev_b32_e32 v1, 13, v7
	v_lshlrev_b32_e32 v2, 6, v21
	v_or3_b32 v57, v1, v2, v4
	v_lshlrev_b32_e32 v1, 9, v7
	v_or_b32_e32 v6, 0x100, v0
	v_or_b32_e32 v18, 0x200, v0
	v_or_b32_e32 v20, 0x300, v0
	v_mad_u32_u24 v1, v19, s8, v1
	v_accvgpr_write_b32 a4, 0
	v_accvgpr_write_b32 a5, 0
	v_accvgpr_write_b32 a6, 0
	s_waitcnt vmcnt(1)
	v_lshl_or_b32 v58, v21, 2, v1
	v_mov_b32_e32 v59, 0x358637bd
	s_mov_b32 s14, 0x800000
	v_lshlrev_b32_e32 v60, 2, v0
	v_lshlrev_b32_e32 v61, 2, v6
	s_waitcnt vmcnt(0)
	v_lshlrev_b32_e32 v62, 2, v18
	v_lshlrev_b32_e32 v63, 2, v20
	s_mov_b32 s15, s2
	global_load_dwordx4 a[8:11], v[12:13], off
	global_load_dwordx4 a[12:15], v[14:15], off
	global_load_dwordx4 a[24:27], v[12:13], off offset:1024
	global_load_dwordx4 a[28:31], v[14:15], off offset:1024
	global_load_dwordx4 a[40:43], v[12:13], off offset:2048
	global_load_dwordx4 a[44:47], v[14:15], off offset:2048
	global_load_dwordx4 a[56:59], v[12:13], off offset:3072
	global_load_dwordx4 a[60:63], v[14:15], off offset:3072
	s_lshl_b32 s45, s15, 4
	v_add_u32_e32 v108, s45, v44
	v_ashrrev_i32_e32 v109, 31, v108
	v_lshlrev_b64 v[108:109], 11, v[108:109]
	v_lshl_add_u64 v[108:109], v[8:9], 0, v[108:109]
	global_load_dwordx2 v[100:101], v[108:109], off
	global_load_dwordx2 v[102:103], v[108:109], off offset:512
	global_load_dwordx2 v[104:105], v[108:109], off offset:1024
	global_load_dwordx2 v[106:107], v[108:109], off offset:1536
	s_waitcnt vmcnt(0)
	s_branch .LBB0_751

.LBB0_751:
	s_lshl_b32 s16, s15, 4
	v_add_u32_e32 v24, s16, v44
	v_ashrrev_i32_e32 v25, 31, v24
	v_lshlrev_b64 v[0:1], 11, v[24:25]
	v_lshl_add_u64 v[0:1], v[8:9], 0, v[0:1]
	s_waitcnt vmcnt(1)
	v_mov_b32_e32 v2, v104
	v_mov_b32_e32 v3, v105
	v_mov_b32_e32 v4, v106
	v_mov_b32_e32 v5, v107
	v_mov_b32_e32 v26, v100
	v_mov_b32_e32 v27, v101
	v_mov_b32_e32 v32, v102
	v_mov_b32_e32 v33, v103
	s_add_i32 s0, s16, 0xffffe000
	s_lshr_b32 s0, s0, 11
	s_add_i32 s0, s0, 1
	s_cmpk_gt_i32 s15, 0x1ff
	s_cselect_b32 s0, s0, 0
	s_mul_hi_u32 s1, s0, 0x6000
	s_mulk_i32 s0, 0x6000
	s_add_u32 s0, s12, s0
	s_addc_u32 s1, s13, s1
	s_add_u32 s8, s0, 0x4000
	s_addc_u32 s9, s1, 0
	s_add_u32 s10, s0, 0x3000
	s_addc_u32 s11, s1, 0
	global_load_dwordx4 a[16:19], v60, s[8:9]
	global_load_dwordx4 a[20:23], v60, s[10:11]
	global_load_dwordx4 a[32:35], v61, s[8:9]
	global_load_dwordx4 a[36:39], v61, s[10:11]
	global_load_dwordx4 a[48:51], v62, s[8:9]
	global_load_dwordx4 a[52:55], v62, s[10:11]
	global_load_dwordx4 a[64:67], v63, s[8:9]
	global_load_dwordx4 a[68:71], v63, s[10:11]
	s_mov_b32 s0, 32
	v_accvgpr_write_b32 a0, 0
	v_accvgpr_mov_b32 a1, a6
	v_accvgpr_mov_b32 a2, a5
	v_accvgpr_mov_b32 a3, a4
	s_waitcnt vmcnt(11)
	v_lshlrev_b32_e32 v20, 16, v2
	v_and_b32_e32 v21, 0xffff0000, v2
	s_waitcnt vmcnt(9)
	v_lshlrev_b32_e32 v29, 16, v27
	v_lshlrev_b32_e32 v28, 16, v26
	v_and_b32_e32 v31, 0xffff0000, v27
	v_and_b32_e32 v30, 0xffff0000, v26
	s_waitcnt vmcnt(8)
	v_lshlrev_b32_e32 v27, 16, v33
	v_lshlrev_b32_e32 v26, 16, v32
	v_and_b32_e32 v33, 0xffff0000, v33
	v_and_b32_e32 v32, 0xffff0000, v32
	v_pk_add_f32 v[34:35], v[28:29], v[30:31]
	v_pk_add_f32 v[36:37], v[26:27], v[32:33]
	v_lshlrev_b32_e32 v22, 16, v3
	v_and_b32_e32 v23, 0xffff0000, v3
	v_and_b32_e32 v3, 0xffff0000, v4
	v_add_f32_e32 v2, v34, v35
	v_pk_add_f32 v[34:35], v[36:37], v[36:37] op_sel:[0,1] op_sel_hi:[1,0]
	v_lshlrev_b32_e32 v7, 16, v4
	v_lshlrev_b32_e32 v19, 16, v5
	v_and_b32_e32 v5, 0xffff0000, v5
	v_add_f32_e32 v18, v20, v21
	v_add_f32_e32 v4, v22, v23
	v_add_f32_e32 v6, 0, v2
	v_mov_b32_e32 v35, v3
	v_pk_add_f32 v[36:37], v[18:19], v[4:5]
	v_pk_add_f32 v[34:35], v[6:7], v[34:35]
	s_nop 0
	v_pk_add_f32 v[34:35], v[34:35], v[36:37]
	s_nop 0
	v_add_f32_e32 v2, v34, v35
	v_mov_b32_e32 v4, v2
	s_nop 1
	v_add_f32_dpp v4, v4, v4 quad_perm:[1,0,3,2] row_mask:0xf bank_mask:0xf
	s_nop 1
	v_add_f32_dpp v4, v4, v4 quad_perm:[2,3,0,1] row_mask:0xf bank_mask:0xf
	s_nop 1
	v_add_f32_dpp v4, v4, v4 row_half_mirror row_mask:0xf bank_mask:0xf
	s_nop 1
	v_add_f32_dpp v4, v4, v4 row_mirror row_mask:0xf bank_mask:0xf
	s_nop 0
	v_readlane_b32 s44, v4, 0
	v_readlane_b32 s45, v4, 16
	v_readlane_b32 s46, v4, 32
	v_readlane_b32 s47, v4, 48
	s_nop 1
	v_mov_b32_e32 v4, s44
	v_add_f32_e32 v4, s45, v4
	v_add_f32_e32 v4, s46, v4
	v_add_f32_e32 v4, s47, v4
	v_mov_b32_e32 v2, v4
	v_fmac_f32_e32 v30, 0xba800000, v2
	v_fmac_f32_e32 v31, 0xba800000, v2
	v_fmac_f32_e32 v29, 0xba800000, v2
	v_fmac_f32_e32 v32, 0xba800000, v2
	v_fmac_f32_e32 v33, 0xba800000, v2
	v_fmac_f32_e32 v27, 0xba800000, v2
	v_fmac_f32_e32 v28, 0xba800000, v2
	v_fmac_f32_e32 v26, 0xba800000, v2
	v_mov_b32_e32 v68, v29
	v_mov_b32_e32 v69, v31
	v_mov_b32_e32 v29, v30
	v_mov_b32_e32 v72, v27
	v_mov_b32_e32 v73, v33
	v_mov_b32_e32 v27, v32
	v_pk_mul_f32 v[30:31], v[68:69], v[68:69]
	v_pk_mul_f32 v[32:33], v[28:29], v[28:29]
	v_pk_mul_f32 v[34:35], v[72:73], v[72:73]
	v_pk_mul_f32 v[36:37], v[26:27], v[26:27]
	v_fmac_f32_e32 v20, 0xba800000, v2
	v_fmac_f32_e32 v22, 0xba800000, v2
	v_pk_mov_b32 v[74:75], v[32:33], v[30:31] op_sel:[1,0]
	v_mov_b32_e32 v33, v31
	v_pk_mov_b32 v[30:31], v[36:37], v[34:35] op_sel:[1,0]
	v_mov_b32_e32 v37, v35
	v_fmac_f32_e32 v21, 0xba800000, v2
	v_fmac_f32_e32 v23, 0xba800000, v2
	v_fmac_f32_e32 v5, 0xba800000, v2
	v_fmac_f32_e32 v19, 0xba800000, v2
	v_fmac_f32_e32 v3, 0xba800000, v2
	v_fmac_f32_e32 v7, 0xba800000, v2
	v_mul_f32_e32 v2, v20, v20
	v_mul_f32_e32 v4, v22, v22
	v_pk_add_f32 v[32:33], v[74:75], v[32:33]
	v_pk_add_f32 v[30:31], v[30:31], v[36:37]
	v_pk_fma_f32 v[38:39], v[20:21], v[20:21], v[2:3] op_sel_hi:[1,1,0]
	v_pk_fma_f32 v[70:71], v[22:23], v[22:23], v[4:5] op_sel_hi:[1,1,0]
	v_pk_add_f32 v[32:33], v[32:33], v[32:33] op_sel_hi:[0,1]
	v_pk_add_f32 v[30:31], v[30:31], v[30:31] op_sel_hi:[0,1]
	v_mul_f32_e32 v38, v7, v7
	v_mul_f32_e32 v70, v3, v3
	v_mul_f32_e32 v32, v19, v19
	v_mul_f32_e32 v30, v5, v5
	v_pk_add_f32 v[34:35], v[38:39], v[70:71]
	v_pk_add_f32 v[30:31], v[32:33], v[30:31]
	s_nop 0
	v_pk_add_f32 v[30:31], v[34:35], v[30:31]
	s_nop 0
	v_add_f32_e32 v2, v30, v31
	v_mov_b32_e32 v4, v2
	s_nop 1
	v_add_f32_dpp v4, v4, v4 quad_perm:[1,0,3,2] row_mask:0xf bank_mask:0xf
	s_nop 1
	v_add_f32_dpp v4, v4, v4 quad_perm:[2,3,0,1] row_mask:0xf bank_mask:0xf
	s_nop 1
	v_add_f32_dpp v4, v4, v4 row_half_mirror row_mask:0xf bank_mask:0xf
	s_nop 1
	v_add_f32_dpp v4, v4, v4 row_mirror row_mask:0xf bank_mask:0xf
	s_nop 0
	v_readlane_b32 s44, v4, 0
	v_readlane_b32 s45, v4, 16
	v_readlane_b32 s46, v4, 32
	v_readlane_b32 s47, v4, 48
	s_nop 1
	v_mov_b32_e32 v4, s44
	v_add_f32_e32 v4, s45, v4
	v_add_f32_e32 v4, s46, v4
	v_add_f32_e32 v4, s47, v4
	v_or_b32_e32 v30, 1, v24
	v_ashrrev_i32_e32 v31, 31, v30
	v_lshlrev_b64 v[30:31], 11, v[30:31]
	v_lshl_add_u64 v[30:31], v[8:9], 0, v[30:31]
	global_load_dwordx2 v[32:33], v[30:31], off
	global_load_dwordx2 v[34:35], v[30:31], off offset:512
	global_load_dwordx2 v[38:39], v[30:31], off offset:1024
	global_load_dwordx2 v[36:37], v[30:31], off offset:1536
	s_add_i32 s46, s15, s3
	s_cmpk_lt_i32 s46, 0x400
	s_cselect_b32 s46, s46, s15
	s_lshl_b32 s45, s46, 4
	v_add_u32_e32 v108, s45, v44
	v_ashrrev_i32_e32 v109, 31, v108
	v_lshlrev_b64 v[108:109], 11, v[108:109]
	v_lshl_add_u64 v[108:109], v[8:9], 0, v[108:109]
	global_load_dwordx2 v[100:101], v[108:109], off
	global_load_dwordx2 v[102:103], v[108:109], off offset:512
	global_load_dwordx2 v[104:105], v[108:109], off offset:1024
	global_load_dwordx2 v[106:107], v[108:109], off offset:1536
	v_lshlrev_b64 v[24:25], 10, v[24:25]
	v_mov_b32_e32 v2, v4
	v_fmamk_f32 v2, v2, 0x3a800000, v59
	v_mul_f32_e32 v4, 0x4b800000, v2
	v_cmp_gt_f32_e32 vcc, s14, v2
	s_nop 1
	v_cndmask_b32_e32 v2, v2, v4, vcc
	v_rsq_f32_e32 v2, v2
	s_nop 0
	v_mul_f32_e32 v4, 0x45800000, v2
	v_cndmask_b32_e32 v6, v2, v4, vcc
	v_pk_mul_f32 v[28:29], v[28:29], v[6:7] op_sel_hi:[1,0]
	v_pk_mul_f32 v[30:31], v[68:69], v[6:7] op_sel_hi:[1,0]
	v_accvgpr_read_b32 v40, a8
	v_accvgpr_read_b32 v41, a9
	v_accvgpr_read_b32 v42, a10
	v_accvgpr_read_b32 v43, a11
	v_accvgpr_read_b32 v64, a12
	v_accvgpr_read_b32 v65, a13
	v_accvgpr_read_b32 v66, a14
	v_accvgpr_read_b32 v67, a15
	s_waitcnt vmcnt(8)
	v_pk_fma_f32 v[28:29], v[40:41], v[28:29], v[64:65]
	v_pk_fma_f32 v[68:69], v[42:43], v[30:31], v[66:67]
	v_cvt_pk_bf16_f32 v30, v28, v29
	v_mov_b32_e32 v2, 0
	v_cvt_pk_bf16_f32 v31, v68, v69
	global_store_dwordx2 v[0:1], v[30:31], off
	v_accvgpr_read_b32 v40, a16
	v_accvgpr_read_b32 v41, a17
	v_accvgpr_read_b32 v42, a18
	v_accvgpr_read_b32 v43, a19
	v_accvgpr_read_b32 v64, a20
	v_accvgpr_read_b32 v65, a21
	v_accvgpr_read_b32 v66, a22
	v_accvgpr_read_b32 v67, a23
	v_lshl_add_u64 v[30:31], v[16:17], 0, v[24:25]
	v_pk_mul_f32 v[20:21], v[20:21], v[6:7] op_sel_hi:[1,0]
	v_pk_mul_f32 v[22:23], v[22:23], v[6:7] op_sel_hi:[1,0]
	v_mov_b32_e32 v4, v19
	v_pk_mul_f32 v[4:5], v[4:5], v[6:7] op_sel_hi:[1,0]
	s_waitcnt vmcnt(5)
	v_and_b32_e32 v19, 0xffff0000, v36
	v_pk_add_f32 v[40:41], v[40:41], 1.0 op_sel_hi:[1,0]
	v_pk_add_f32 v[24:25], v[42:43], 1.0 op_sel_hi:[1,0]
	v_pk_fma_f32 v[40:41], v[40:41], v[28:29], v[64:65]
	v_pk_fma_f32 v[42:43], v[24:25], v[68:69], v[66:67]
	v_cvt_pk_fp8_f32 v2, v40, v41
	v_pk_mul_f32 v[24:25], v[26:27], v[6:7] op_sel_hi:[1,0]
	v_cvt_pk_fp8_f32 v2, v42, v43 op_sel:[0,0,1]
	global_store_dword v[30:31], v2, off
	v_accvgpr_read_b32 v64, a24
	v_accvgpr_read_b32 v65, a25
	v_accvgpr_read_b32 v66, a26
	v_accvgpr_read_b32 v67, a27
	v_accvgpr_read_b32 v68, a28
	v_accvgpr_read_b32 v69, a29
	v_accvgpr_read_b32 v70, a30
	v_accvgpr_read_b32 v71, a31
	v_pk_mul_f32 v[26:27], v[72:73], v[6:7] op_sel_hi:[1,0]
	ds_write_b128 v54, v[40:43]
	v_mov_b32_e32 v2, 0
	v_pk_fma_f32 v[28:29], v[66:67], v[26:27], v[70:71]
	v_pk_fma_f32 v[64:65], v[64:65], v[24:25], v[68:69]
	s_nop 0
	v_cvt_pk_bf16_f32 v24, v64, v65
	v_cvt_pk_bf16_f32 v25, v28, v29
	global_store_dwordx2 v[0:1], v[24:25], off offset:512
	v_accvgpr_read_b32 v24, a32
	v_accvgpr_read_b32 v25, a33
	v_accvgpr_read_b32 v26, a34
	v_accvgpr_read_b32 v27, a35
	s_nop 0
	v_accvgpr_read_b32 v40, a36
	v_accvgpr_read_b32 v41, a37
	v_accvgpr_read_b32 v42, a38
	v_accvgpr_read_b32 v43, a39
	v_pk_add_f32 v[24:25], v[24:25], 1.0 op_sel_hi:[1,0]
	v_pk_add_f32 v[26:27], v[26:27], 1.0 op_sel_hi:[1,0]
	v_pk_fma_f32 v[24:25], v[24:25], v[64:65], v[40:41]
	v_pk_fma_f32 v[26:27], v[26:27], v[28:29], v[42:43]
	v_cvt_pk_fp8_f32 v2, v24, v25
	s_nop 0
	v_cvt_pk_fp8_f32 v2, v26, v27 op_sel:[0,0,1]
	global_store_dword v[30:31], v2, off offset:256
	v_accvgpr_read_b32 v40, a40
	v_accvgpr_read_b32 v41, a41
	v_accvgpr_read_b32 v42, a42
	v_accvgpr_read_b32 v43, a43
	v_accvgpr_read_b32 v64, a44
	v_accvgpr_read_b32 v65, a45
	v_accvgpr_read_b32 v66, a46
	v_accvgpr_read_b32 v67, a47
	ds_write_b128 v54, v[24:27] offset:1024
	v_mov_b32_e32 v2, 0
	v_pk_fma_f32 v[28:29], v[22:23], v[42:43], v[66:67]
	v_pk_fma_f32 v[40:41], v[20:21], v[40:41], v[64:65]
	s_nop 0
	v_cvt_pk_bf16_f32 v20, v40, v41
	v_cvt_pk_bf16_f32 v21, v28, v29
	global_store_dwordx2 v[0:1], v[20:21], off offset:1024
	v_accvgpr_read_b32 v20, a48
	v_accvgpr_read_b32 v21, a49
	v_accvgpr_read_b32 v22, a50
	v_accvgpr_read_b32 v23, a51
	s_nop 0
	v_accvgpr_read_b32 v24, a52
	v_accvgpr_read_b32 v25, a53
	v_accvgpr_read_b32 v26, a54
	v_accvgpr_read_b32 v27, a55
	v_pk_add_f32 v[20:21], v[20:21], 1.0 op_sel_hi:[1,0]
	v_pk_add_f32 v[22:23], v[22:23], 1.0 op_sel_hi:[1,0]
	v_pk_fma_f32 v[20:21], v[40:41], v[20:21], v[24:25]
	v_pk_fma_f32 v[22:23], v[28:29], v[22:23], v[26:27]
	v_cvt_pk_fp8_f32 v2, v20, v21
	v_lshlrev_b32_e32 v26, 16, v38
	v_cvt_pk_fp8_f32 v2, v22, v23 op_sel:[0,0,1]
	global_store_dword v[30:31], v2, off offset:512
	v_accvgpr_read_b32 v64, a56
	v_accvgpr_read_b32 v65, a57
	v_accvgpr_read_b32 v66, a58
	v_accvgpr_read_b32 v67, a59
	v_accvgpr_read_b32 v68, a60
	v_accvgpr_read_b32 v69, a61
	v_accvgpr_read_b32 v70, a62
	v_accvgpr_read_b32 v71, a63
	v_mov_b32_e32 v2, v7
	v_pk_mul_f32 v[2:3], v[2:3], v[6:7] op_sel_hi:[1,0]
	ds_write_b128 v54, v[20:23] offset:2048
	v_and_b32_e32 v27, 0xffff0000, v38
	v_lshlrev_b32_e32 v28, 16, v39
	v_and_b32_e32 v29, 0xffff0000, v39
	v_lshlrev_b32_e32 v23, 16, v36
	v_lshlrev_b32_e32 v25, 16, v37
	v_and_b32_e32 v21, 0xffff0000, v37
	v_lshlrev_b32_e32 v37, 16, v33
	v_lshlrev_b32_e32 v36, 16, v32
	v_and_b32_e32 v39, 0xffff0000, v33
	v_and_b32_e32 v38, 0xffff0000, v32
	v_lshlrev_b32_e32 v33, 16, v35
	v_lshlrev_b32_e32 v32, 16, v34
	v_and_b32_e32 v35, 0xffff0000, v35
	v_and_b32_e32 v34, 0xffff0000, v34
	v_add_f32_e32 v24, v26, v27
	v_add_f32_e32 v20, v28, v29
	v_pk_fma_f32 v[40:41], v[4:5], v[66:67], v[70:71]
	v_pk_fma_f32 v[42:43], v[2:3], v[64:65], v[68:69]
	v_pk_add_f32 v[64:65], v[36:37], v[38:39]
	v_cvt_pk_bf16_f32 v2, v42, v43
	v_cvt_pk_bf16_f32 v3, v40, v41
	global_store_dwordx2 v[0:1], v[2:3], off offset:1536
	v_accvgpr_read_b32 v0, a64
	v_accvgpr_read_b32 v1, a65
	v_accvgpr_read_b32 v2, a66
	v_accvgpr_read_b32 v3, a67
	v_pk_add_f32 v[66:67], v[32:33], v[34:35]
	v_accvgpr_read_b32 v4, a68
	v_accvgpr_read_b32 v5, a69
	v_accvgpr_read_b32 v6, a70
	v_accvgpr_read_b32 v7, a71
	v_add_f32_e32 v18, v64, v65
	v_pk_add_f32 v[64:65], v[66:67], v[66:67] op_sel:[0,1] op_sel_hi:[1,0]
	v_add_f32_e32 v22, 0, v18
	v_mov_b32_e32 v65, v19
	v_pk_add_f32 v[66:67], v[24:25], v[20:21]
	v_pk_add_f32 v[64:65], v[22:23], v[64:65]
	v_mov_b32_e32 v22, 0
	v_pk_add_f32 v[64:65], v[64:65], v[66:67]
	v_pk_add_f32 v[0:1], v[0:1], 1.0 op_sel_hi:[1,0]
	v_add_f32_e32 v18, v64, v65
	ds_bpermute_b32 v20, v45, v18
	v_pk_add_f32 v[2:3], v[2:3], 1.0 op_sel_hi:[1,0]
	v_pk_fma_f32 v[64:65], v[42:43], v[0:1], v[4:5]
	v_pk_fma_f32 v[66:67], v[40:41], v[2:3], v[6:7]
	v_cvt_pk_fp8_f32 v22, v64, v65
	s_waitcnt lgkmcnt(0)
	v_add_f32_e32 v18, v18, v20
	ds_bpermute_b32 v20, v46, v18
	v_cvt_pk_fp8_f32 v22, v66, v67 op_sel:[0,0,1]
	global_store_dword v[30:31], v22, off offset:768
	v_accvgpr_read_b32 v40, a8
	v_accvgpr_read_b32 v41, a9
	v_accvgpr_read_b32 v42, a10
	v_accvgpr_read_b32 v43, a11
	v_accvgpr_read_b32 v68, a12
	v_accvgpr_read_b32 v69, a13
	v_accvgpr_read_b32 v70, a14
	v_accvgpr_read_b32 v71, a15
	ds_write_b128 v54, v[64:67] offset:3072
	s_waitcnt lgkmcnt(1)
	v_add_f32_e32 v18, v18, v20
	ds_bpermute_b32 v20, v47, v18
	s_waitcnt lgkmcnt(0)
	v_add_f32_e32 v18, v18, v20
	ds_bpermute_b32 v20, v48, v18
	s_waitcnt lgkmcnt(0)
	v_add_f32_e32 v18, v18, v20
	ds_bpermute_b32 v20, v49, v18
	s_waitcnt lgkmcnt(0)
	v_add_f32_e32 v18, v18, v20
	ds_bpermute_b32 v20, v50, v18
	s_waitcnt lgkmcnt(0)
	v_add_f32_e32 v18, v18, v20
	v_fmac_f32_e32 v38, 0xba800000, v18
	v_fmac_f32_e32 v39, 0xba800000, v18
	v_fmac_f32_e32 v37, 0xba800000, v18
	v_fmac_f32_e32 v34, 0xba800000, v18
	v_fmac_f32_e32 v35, 0xba800000, v18
	v_fmac_f32_e32 v33, 0xba800000, v18
	v_fmac_f32_e32 v36, 0xba800000, v18
	v_fmac_f32_e32 v32, 0xba800000, v18
	v_fmac_f32_e32 v26, 0xba800000, v18
	v_fmac_f32_e32 v28, 0xba800000, v18
	v_mov_b32_e32 v0, v37
	v_mov_b32_e32 v1, v39
	v_mov_b32_e32 v37, v38
	v_mov_b32_e32 v6, v33
	v_mov_b32_e32 v7, v35
	v_mov_b32_e32 v33, v34
	v_fmac_f32_e32 v27, 0xba800000, v18
	v_fmac_f32_e32 v29, 0xba800000, v18
	v_mul_f32_e32 v2, v26, v26
	v_mul_f32_e32 v4, v28, v28
	v_pk_mul_f32 v[30:31], v[0:1], v[0:1]
	v_pk_mul_f32 v[34:35], v[36:37], v[36:37]
	v_pk_mul_f32 v[38:39], v[6:7], v[6:7]
	v_pk_mul_f32 v[72:73], v[32:33], v[32:33]
	v_fmac_f32_e32 v19, 0xba800000, v18
	v_fmac_f32_e32 v23, 0xba800000, v18
	v_pk_fma_f32 v[2:3], v[26:27], v[26:27], v[2:3] op_sel_hi:[1,1,0]
	v_pk_fma_f32 v[4:5], v[28:29], v[28:29], v[4:5] op_sel_hi:[1,1,0]
	v_pk_mov_b32 v[74:75], v[34:35], v[30:31] op_sel:[1,0]
	v_mov_b32_e32 v35, v31
	v_pk_mov_b32 v[30:31], v[72:73], v[38:39] op_sel:[1,0]
	v_mov_b32_e32 v73, v39
	v_mul_f32_e32 v2, v23, v23
	v_mul_f32_e32 v4, v19, v19
	v_pk_add_f32 v[34:35], v[74:75], v[34:35]
	v_pk_add_f32 v[30:31], v[30:31], v[72:73]
	v_fmac_f32_e32 v21, 0xba800000, v18
	v_fmac_f32_e32 v25, 0xba800000, v18
	v_pk_add_f32 v[2:3], v[2:3], v[4:5]
	v_pk_add_f32 v[4:5], v[34:35], v[34:35] op_sel_hi:[0,1]
	v_pk_add_f32 v[30:31], v[30:31], v[30:31] op_sel_hi:[0,1]
	v_mul_f32_e32 v4, v25, v25
	v_mul_f32_e32 v30, v21, v21
	v_pk_add_f32 v[4:5], v[4:5], v[30:31]
	v_add_u32_e32 v30, s16, v55
	v_pk_add_f32 v[2:3], v[2:3], v[4:5]
	v_ashrrev_i32_e32 v31, 31, v30
	v_add_f32_e32 v2, v2, v3
	v_mov_b32_e32 v3, v2
	s_nop 1
	v_add_f32_dpp v3, v3, v3 quad_perm:[1,0,3,2] row_mask:0xf bank_mask:0xf
	s_nop 1
	v_add_f32_dpp v3, v3, v3 quad_perm:[2,3,0,1] row_mask:0xf bank_mask:0xf
	s_nop 1
	v_add_f32_dpp v3, v3, v3 row_half_mirror row_mask:0xf bank_mask:0xf
	s_nop 1
	v_add_f32_dpp v3, v3, v3 row_mirror row_mask:0xf bank_mask:0xf
	s_nop 0
	v_readlane_b32 s44, v3, 0
	v_readlane_b32 s45, v3, 16
	v_readlane_b32 s46, v3, 32
	v_readlane_b32 s47, v3, 48
	s_nop 1
	v_mov_b32_e32 v3, s44
	v_add_f32_e32 v3, s45, v3
	v_add_f32_e32 v3, s46, v3
	v_add_f32_e32 v3, s47, v3
	v_mov_b32_e32 v18, v23
	v_mov_b32_e32 v20, v25
	v_mov_b32_e32 v2, v3
	v_fmamk_f32 v2, v2, 0x3a800000, v59
	v_mul_f32_e32 v3, 0x4b800000, v2
	v_cmp_gt_f32_e32 vcc, s14, v2
	s_nop 1
	v_cndmask_b32_e32 v2, v2, v3, vcc
	v_rsq_f32_e32 v4, v2
	v_lshlrev_b64 v[2:3], 11, v[30:31]
	v_lshl_add_u64 v[2:3], v[8:9], 0, v[2:3]
	v_mul_f32_e32 v5, 0x45800000, v4
	v_cndmask_b32_e32 v4, v4, v5, vcc
	v_pk_mul_f32 v[34:35], v[36:37], v[4:5] op_sel_hi:[1,0]
	v_pk_mul_f32 v[0:1], v[0:1], v[4:5] op_sel_hi:[1,0]
	v_pk_fma_f32 v[64:65], v[40:41], v[34:35], v[68:69]
	v_pk_fma_f32 v[42:43], v[42:43], v[0:1], v[70:71]
	v_cvt_pk_bf16_f32 v0, v64, v65
	v_mov_b32_e32 v5, 0
	v_cvt_pk_bf16_f32 v1, v42, v43
	global_store_dwordx2 v[2:3], v[0:1], off
	v_accvgpr_read_b32 v34, a16
	v_accvgpr_read_b32 v35, a17
	v_accvgpr_read_b32 v36, a18
	v_accvgpr_read_b32 v37, a19
	v_accvgpr_read_b32 v38, a20
	v_accvgpr_read_b32 v39, a21
	v_accvgpr_read_b32 v40, a22
	v_accvgpr_read_b32 v41, a23
	v_lshlrev_b64 v[0:1], 10, v[30:31]
	v_lshl_add_u64 v[0:1], v[16:17], 0, v[0:1]
	v_pk_add_f32 v[34:35], v[34:35], 1.0 op_sel_hi:[1,0]
	v_pk_add_f32 v[30:31], v[36:37], 1.0 op_sel_hi:[1,0]
	v_pk_fma_f32 v[34:35], v[34:35], v[64:65], v[38:39]
	v_pk_fma_f32 v[36:37], v[30:31], v[42:43], v[40:41]
	v_cvt_pk_fp8_f32 v5, v34, v35
	s_nop 0
	v_cvt_pk_fp8_f32 v5, v36, v37 op_sel:[0,0,1]
	global_store_dword v[0:1], v5, off
	v_accvgpr_read_b32 v38, a24
	v_accvgpr_read_b32 v39, a25
	v_accvgpr_read_b32 v40, a26
	v_accvgpr_read_b32 v41, a27
	v_accvgpr_read_b32 v64, a28
	v_accvgpr_read_b32 v65, a29
	v_accvgpr_read_b32 v66, a30
	v_accvgpr_read_b32 v67, a31
	v_pk_mul_f32 v[30:31], v[32:33], v[4:5] op_sel_hi:[1,0]
	v_pk_mul_f32 v[6:7], v[6:7], v[4:5] op_sel_hi:[1,0]
	ds_write_b128 v56, v[34:37]
	v_mov_b32_e32 v5, 0
	v_pk_fma_f32 v[6:7], v[40:41], v[6:7], v[66:67]
	v_pk_fma_f32 v[38:39], v[38:39], v[30:31], v[64:65]
	s_nop 0
	v_cvt_pk_bf16_f32 v30, v38, v39
	v_cvt_pk_bf16_f32 v31, v6, v7
	global_store_dwordx2 v[2:3], v[30:31], off offset:512
	v_accvgpr_read_b32 v30, a32
	v_accvgpr_read_b32 v31, a33
	v_accvgpr_read_b32 v32, a34
	v_accvgpr_read_b32 v33, a35
	s_nop 0
	v_accvgpr_read_b32 v34, a36
	v_accvgpr_read_b32 v35, a37
	v_accvgpr_read_b32 v36, a38
	v_accvgpr_read_b32 v37, a39
	v_pk_add_f32 v[30:31], v[30:31], 1.0 op_sel_hi:[1,0]
	v_pk_add_f32 v[32:33], v[32:33], 1.0 op_sel_hi:[1,0]
	v_pk_fma_f32 v[30:31], v[30:31], v[38:39], v[34:35]
	v_pk_fma_f32 v[32:33], v[32:33], v[6:7], v[36:37]
	v_cvt_pk_fp8_f32 v5, v30, v31
	s_nop 0
	v_cvt_pk_fp8_f32 v5, v32, v33 op_sel:[0,0,1]
	global_store_dword v[0:1], v5, off offset:256
	v_accvgpr_read_b32 v34, a40
	v_accvgpr_read_b32 v35, a41
	v_accvgpr_read_b32 v36, a42
	v_accvgpr_read_b32 v37, a43
	v_accvgpr_read_b32 v38, a44
	v_accvgpr_read_b32 v39, a45
	v_accvgpr_read_b32 v40, a46
	v_accvgpr_read_b32 v41, a47
	v_pk_mul_f32 v[6:7], v[26:27], v[4:5] op_sel_hi:[1,0]
	v_pk_mul_f32 v[26:27], v[28:29], v[4:5] op_sel_hi:[1,0]
	ds_write_b128 v56, v[30:33] offset:1024
	v_mov_b32_e32 v5, 0
	v_pk_fma_f32 v[36:37], v[26:27], v[36:37], v[40:41]
	v_pk_fma_f32 v[6:7], v[6:7], v[34:35], v[38:39]
	s_nop 0
	v_cvt_pk_bf16_f32 v26, v6, v7
	v_cvt_pk_bf16_f32 v27, v36, v37
	global_store_dwordx2 v[2:3], v[26:27], off offset:1024
	v_accvgpr_read_b32 v26, a48
	v_accvgpr_read_b32 v27, a49
	v_accvgpr_read_b32 v28, a50
	v_accvgpr_read_b32 v29, a51
	s_nop 0
	v_accvgpr_read_b32 v30, a52
	v_accvgpr_read_b32 v31, a53
	v_accvgpr_read_b32 v32, a54
	v_accvgpr_read_b32 v33, a55
	v_pk_add_f32 v[26:27], v[26:27], 1.0 op_sel_hi:[1,0]
	v_pk_add_f32 v[28:29], v[28:29], 1.0 op_sel_hi:[1,0]
	v_pk_fma_f32 v[26:27], v[6:7], v[26:27], v[30:31]
	v_pk_fma_f32 v[28:29], v[36:37], v[28:29], v[32:33]
	v_cvt_pk_fp8_f32 v5, v26, v27
	s_nop 0
	v_cvt_pk_fp8_f32 v5, v28, v29 op_sel:[0,0,1]
	global_store_dword v[0:1], v5, off offset:512
	v_accvgpr_read_b32 v30, a56
	v_accvgpr_read_b32 v31, a57
	v_accvgpr_read_b32 v32, a58
	v_accvgpr_read_b32 v33, a59
	v_accvgpr_read_b32 v34, a60
	v_accvgpr_read_b32 v35, a61
	v_accvgpr_read_b32 v36, a62
	v_accvgpr_read_b32 v37, a63
	v_pk_mul_f32 v[6:7], v[18:19], v[4:5] op_sel_hi:[1,0]
	v_pk_mul_f32 v[4:5], v[20:21], v[4:5] op_sel_hi:[1,0]
	ds_write_b128 v56, v[26:29] offset:2048
	v_mov_b32_e32 v26, 0
	v_pk_fma_f32 v[22:23], v[4:5], v[32:33], v[36:37]
	v_pk_fma_f32 v[24:25], v[6:7], v[30:31], v[34:35]
	s_nop 0
	v_cvt_pk_bf16_f32 v4, v24, v25
	v_cvt_pk_bf16_f32 v5, v22, v23
	global_store_dwordx2 v[2:3], v[4:5], off offset:1536
	v_accvgpr_read_b32 v4, a64
	v_accvgpr_read_b32 v5, a65
	v_accvgpr_read_b32 v6, a66
	v_accvgpr_read_b32 v7, a67
	s_nop 0
	v_accvgpr_read_b32 v18, a68
	v_accvgpr_read_b32 v19, a69
	v_accvgpr_read_b32 v20, a70
	v_accvgpr_read_b32 v21, a71
	v_mov_b32_e32 v2, v58
	v_mov_b32_e32 v3, v57
	v_pk_add_f32 v[6:7], v[6:7], 1.0 op_sel_hi:[1,0]
	v_pk_add_f32 v[4:5], v[4:5], 1.0 op_sel_hi:[1,0]
	v_pk_fma_f32 v[6:7], v[22:23], v[6:7], v[20:21]
	v_pk_fma_f32 v[4:5], v[24:25], v[4:5], v[18:19]
	s_nop 0
	v_cvt_pk_fp8_f32 v26, v4, v5
	s_nop 0
	v_cvt_pk_fp8_f32 v26, v6, v7 op_sel:[0,0,1]
	ds_write_b128 v56, v[4:7] offset:3072
	global_store_dword v[0:1], v26, off offset:768
	s_waitcnt lgkmcnt(0)
	s_barrier

.LBB0_1349:
	s_or_b64 exec, exec, s[0:1]
	s_cmpk_gt_i32 s2, 0x3ff
	s_cbranch_scc1 .LBB0_1356
	v_readlane_b32 s12, v126, 2
	v_readlane_b32 s13, v126, 3
	v_readlane_b32 s14, v126, 4
	v_readlane_b32 s15, v126, 5
	v_readlane_b32 s16, v126, 6
	v_readlane_b32 s17, v126, 7
	v_and_b32_e32 v6, 63, v2
	v_readlane_b32 s18, v126, 8
	v_readlane_b32 s19, v126, 9
	s_mov_b64 s[12:13], s[16:17]
	v_mov_b32_e32 v1, 0
	s_mov_b64 s[14:15], s[18:19]
	v_lshlrev_b32_e32 v4, 3, v6
	v_mov_b32_e32 v5, v1
	v_mbcnt_lo_u32_b32 v3, -1, 0
	v_lshl_add_u64 v[4:5], s[14:15], 0, v[4:5]
	s_mov_b64 s[4:5], 0x1d3e8000
	v_mbcnt_hi_u32_b32 v3, -1, v3
	v_lshl_add_u64 v[8:9], v[4:5], 0, s[4:5]
	v_and_b32_e32 v4, 64, v3
	v_add_u32_e32 v4, 64, v4
	v_xor_b32_e32 v5, 1, v3
	v_cmp_lt_i32_e32 vcc, v5, v4
	s_add_u32 s0, s52, 0x1000
	s_addc_u32 s1, s53, 0
	v_cndmask_b32_e32 v5, v3, v5, vcc
	v_lshlrev_b32_e32 v57, 2, v5
	v_xor_b32_e32 v5, 2, v3
	v_cmp_lt_i32_e32 vcc, v5, v4
	s_add_u32 s8, s50, 0x1000
	s_addc_u32 s9, s51, 0
	v_cndmask_b32_e32 v5, v3, v5, vcc
	v_lshlrev_b32_e32 v58, 2, v5
	v_xor_b32_e32 v5, 4, v3
	v_cmp_lt_i32_e32 vcc, v5, v4
	s_add_u32 s12, s14, 0x18e80000
	v_ashrrev_i32_e32 v7, 6, v2
	v_cndmask_b32_e32 v5, v3, v5, vcc
	v_lshlrev_b32_e32 v59, 2, v5
	v_xor_b32_e32 v5, 8, v3
	v_cmp_lt_i32_e32 vcc, v5, v4
	s_addc_u32 s13, s15, 0
	v_and_b32_e32 v31, 15, v2
	v_cndmask_b32_e32 v5, v3, v5, vcc
	v_lshlrev_b32_e32 v60, 2, v5
	v_xor_b32_e32 v5, 16, v3
	v_cmp_lt_i32_e32 vcc, v5, v4
	v_bfe_u32 v33, v2, 4, 2
	s_add_i32 s10, 0, 0x20100
	v_cndmask_b32_e32 v5, v3, v5, vcc
	v_lshlrev_b32_e32 v61, 2, v5
	v_xor_b32_e32 v5, 32, v3
	v_cmp_lt_i32_e32 vcc, v5, v4
	v_lshlrev_b32_e32 v4, 2, v31
	s_movk_i32 s4, 0x100
	v_cndmask_b32_e32 v3, v3, v5, vcc
	v_lshlrev_b32_e32 v62, 2, v3
	v_lshl_add_u32 v3, v7, 10, s10
	v_lshlrev_b32_e32 v5, 8, v33
	v_add3_u32 v63, v3, v5, v4
	v_mov_b32_e32 v5, v1
	v_lshlrev_b32_e32 v0, 2, v6
	v_cmp_gt_i32_e64 s[4:5], s4, v2
	v_lshl_add_u32 v64, v2, 2, s10
	v_ashrrev_i32_e32 v65, 4, v2
	v_lshl_add_u64 v[2:3], s[14:15], 0, v[4:5]
	s_mov_b64 s[10:11], 0x18fc8000
	v_lshl_add_u64 v[10:11], v[2:3], 0, s[10:11]
	v_lshlrev_b32_e32 v2, 4, v6
	v_or_b32_e32 v6, 0x100, v0
	v_or_b32_e32 v30, 0x200, v0
	v_or_b32_e32 v32, 0x300, v0
	v_lshlrev_b32_e32 v56, 1, v7
	v_mov_b32_e32 v3, v1
	v_lshlrev_b32_e32 v18, 2, v6
	v_mov_b32_e32 v19, v1
	v_lshlrev_b32_e32 v22, 2, v30
	v_mov_b32_e32 v23, v1
	v_lshlrev_b32_e32 v26, 2, v32
	v_mov_b32_e32 v27, v1
	s_movk_i32 s10, 0x2020
	v_lshl_add_u64 v[12:13], s[8:9], 0, v[2:3]
	v_lshl_add_u64 v[16:17], s[8:9], 0, v[18:19]
	v_lshl_add_u64 v[20:21], s[8:9], 0, v[22:23]
	v_lshl_add_u64 v[24:25], s[8:9], 0, v[26:27]
	v_or_b32_e32 v67, 1, v56
	s_movk_i32 s8, 0x1010
	v_mul_lo_u32 v5, v7, s10
	s_add_i32 s10, 0, 0x10000
	v_lshl_add_u64 v[14:15], s[0:1], 0, v[2:3]
	v_mul_lo_u32 v3, v67, s8
	v_add3_u32 v66, s10, v5, v2
	v_lshl_add_u64 v[18:19], s[0:1], 0, v[18:19]
	v_lshl_add_u64 v[22:23], s[0:1], 0, v[22:23]
	v_lshl_add_u64 v[26:27], s[0:1], 0, v[26:27]
	v_add3_u32 v68, s10, v3, v2
	v_lshl_add_u64 v[2:3], s[14:15], 0, v[0:1]
	s_mov_b64 s[0:1], 0x1b3e8000
	v_lshl_add_u64 v[28:29], v[2:3], 0, s[0:1]
	v_lshlrev_b32_e32 v1, 13, v7
	v_lshlrev_b32_e32 v2, 6, v33
	v_or3_b32 v69, v1, v2, v4
	v_lshlrev_b32_e32 v1, 9, v7
	v_mad_u32_u24 v1, v31, s8, v1
	v_accvgpr_write_b32 a4, 0
	v_accvgpr_write_b32 a5, 0
	v_accvgpr_write_b32 a6, 0
	v_lshl_or_b32 v70, v33, 2, v1
	v_mov_b32_e32 v71, 0x358637bd
	s_mov_b32 s14, 0x800000
	v_lshlrev_b32_e32 v72, 2, v0
	v_lshlrev_b32_e32 v73, 2, v6
	v_lshlrev_b32_e32 v74, 2, v30
	v_lshlrev_b32_e32 v75, 2, v32
	s_mov_b32 s15, s2
	global_load_dwordx4 a[8:11], v[12:13], off
	global_load_dwordx4 a[12:15], v[14:15], off
	global_load_dwordx4 a[24:27], v[16:17], off
	global_load_dwordx4 a[28:31], v[18:19], off
	global_load_dwordx4 a[40:43], v[20:21], off
	global_load_dwordx4 a[44:47], v[22:23], off
	global_load_dwordx4 a[56:59], v[24:25], off
	global_load_dwordx4 a[60:63], v[26:27], off
	s_lshl_b32 s45, s15, 4
	v_add_u32_e32 v108, s45, v56
	v_ashrrev_i32_e32 v109, 31, v108
	v_lshlrev_b64 v[108:109], 11, v[108:109]
	v_lshl_add_u64 v[108:109], v[8:9], 0, v[108:109]
	global_load_dwordx2 v[100:101], v[108:109], off
	global_load_dwordx2 v[102:103], v[108:109], off offset:512
	global_load_dwordx2 v[104:105], v[108:109], off offset:1024
	global_load_dwordx2 v[106:107], v[108:109], off offset:1536
	s_waitcnt vmcnt(0)
	s_branch .LBB0_1352

.LBB0_1352:
	s_lshl_b32 s16, s15, 4
	v_add_u32_e32 v36, s16, v56
	v_ashrrev_i32_e32 v37, 31, v36
	v_lshlrev_b64 v[0:1], 11, v[36:37]
	v_lshl_add_u64 v[0:1], v[8:9], 0, v[0:1]
	s_waitcnt vmcnt(1)
	v_mov_b32_e32 v2, v104
	v_mov_b32_e32 v3, v105
	v_mov_b32_e32 v4, v106
	v_mov_b32_e32 v5, v107
	v_mov_b32_e32 v38, v100
	v_mov_b32_e32 v39, v101
	v_mov_b32_e32 v44, v102
	v_mov_b32_e32 v45, v103
	s_add_i32 s0, s16, 0xffffe000
	s_lshr_b32 s0, s0, 11
	s_add_i32 s0, s0, 6
	s_cmpk_gt_i32 s15, 0x1ff
	s_cselect_b32 s0, s0, 5
	s_mul_hi_u32 s1, s0, 0x6000
	s_mulk_i32 s0, 0x6000
	s_add_u32 s0, s12, s0
	s_addc_u32 s1, s13, s1
	s_add_u32 s10, s0, 0x4000
	s_addc_u32 s11, s1, 0
	s_add_u32 s8, s0, 0x3000
	s_addc_u32 s9, s1, 0
	global_load_dwordx4 a[16:19], v72, s[10:11]
	global_load_dwordx4 a[20:23], v72, s[8:9]
	global_load_dwordx4 a[32:35], v73, s[10:11]
	global_load_dwordx4 a[36:39], v73, s[8:9]
	global_load_dwordx4 a[48:51], v74, s[10:11]
	global_load_dwordx4 a[52:55], v74, s[8:9]
	global_load_dwordx4 a[64:67], v75, s[10:11]
	global_load_dwordx4 a[68:71], v75, s[8:9]
	s_mov_b32 s0, 32
	v_accvgpr_write_b32 a0, 0
	v_accvgpr_mov_b32 a1, a6
	v_accvgpr_mov_b32 a2, a5
	v_accvgpr_mov_b32 a3, a4
	s_waitcnt vmcnt(11)
	v_lshlrev_b32_e32 v32, 16, v2
	v_and_b32_e32 v33, 0xffff0000, v2
	s_waitcnt vmcnt(9)
	v_lshlrev_b32_e32 v41, 16, v39
	v_lshlrev_b32_e32 v40, 16, v38
	v_and_b32_e32 v43, 0xffff0000, v39
	v_and_b32_e32 v42, 0xffff0000, v38
	s_waitcnt vmcnt(8)
	v_lshlrev_b32_e32 v39, 16, v45
	v_lshlrev_b32_e32 v38, 16, v44
	v_and_b32_e32 v45, 0xffff0000, v45
	v_and_b32_e32 v44, 0xffff0000, v44
	v_pk_add_f32 v[46:47], v[40:41], v[42:43]
	v_pk_add_f32 v[48:49], v[38:39], v[44:45]
	v_lshlrev_b32_e32 v34, 16, v3
	v_and_b32_e32 v35, 0xffff0000, v3
	v_and_b32_e32 v3, 0xffff0000, v4
	v_add_f32_e32 v2, v46, v47
	v_pk_add_f32 v[46:47], v[48:49], v[48:49] op_sel:[0,1] op_sel_hi:[1,0]
	v_lshlrev_b32_e32 v7, 16, v4
	v_lshlrev_b32_e32 v31, 16, v5
	v_and_b32_e32 v5, 0xffff0000, v5
	v_add_f32_e32 v30, v32, v33
	v_add_f32_e32 v4, v34, v35
	v_add_f32_e32 v6, 0, v2
	v_mov_b32_e32 v47, v3
	v_pk_add_f32 v[48:49], v[30:31], v[4:5]
	v_pk_add_f32 v[46:47], v[6:7], v[46:47]
	s_nop 0
	v_pk_add_f32 v[46:47], v[46:47], v[48:49]
	s_nop 0
	v_add_f32_e32 v2, v46, v47
	v_mov_b32_e32 v4, v2
	s_nop 1
	v_add_f32_dpp v4, v4, v4 quad_perm:[1,0,3,2] row_mask:0xf bank_mask:0xf
	s_nop 1
	v_add_f32_dpp v4, v4, v4 quad_perm:[2,3,0,1] row_mask:0xf bank_mask:0xf
	s_nop 1
	v_add_f32_dpp v4, v4, v4 row_half_mirror row_mask:0xf bank_mask:0xf
	s_nop 1
	v_add_f32_dpp v4, v4, v4 row_mirror row_mask:0xf bank_mask:0xf
	s_nop 0
	v_readlane_b32 s44, v4, 0
	v_readlane_b32 s45, v4, 16
	v_readlane_b32 s46, v4, 32
	v_readlane_b32 s47, v4, 48
	s_nop 1
	v_mov_b32_e32 v4, s44
	v_add_f32_e32 v4, s45, v4
	v_add_f32_e32 v4, s46, v4
	v_add_f32_e32 v4, s47, v4
	v_mov_b32_e32 v2, v4
	v_fmac_f32_e32 v42, 0xba800000, v2
	v_fmac_f32_e32 v43, 0xba800000, v2
	v_fmac_f32_e32 v41, 0xba800000, v2
	v_fmac_f32_e32 v44, 0xba800000, v2
	v_fmac_f32_e32 v45, 0xba800000, v2
	v_fmac_f32_e32 v39, 0xba800000, v2
	v_fmac_f32_e32 v40, 0xba800000, v2
	v_fmac_f32_e32 v38, 0xba800000, v2
	v_mov_b32_e32 v82, v41
	v_mov_b32_e32 v83, v43
	v_mov_b32_e32 v41, v42
	v_mov_b32_e32 v86, v39
	v_mov_b32_e32 v87, v45
	v_mov_b32_e32 v39, v44
	v_pk_mul_f32 v[42:43], v[82:83], v[82:83]
	v_pk_mul_f32 v[44:45], v[40:41], v[40:41]
	v_pk_mul_f32 v[46:47], v[86:87], v[86:87]
	v_pk_mul_f32 v[48:49], v[38:39], v[38:39]
	v_fmac_f32_e32 v32, 0xba800000, v2
	v_fmac_f32_e32 v34, 0xba800000, v2
	v_pk_mov_b32 v[88:89], v[44:45], v[42:43] op_sel:[1,0]
	v_mov_b32_e32 v45, v43
	v_pk_mov_b32 v[42:43], v[48:49], v[46:47] op_sel:[1,0]
	v_mov_b32_e32 v49, v47
	v_fmac_f32_e32 v33, 0xba800000, v2
	v_fmac_f32_e32 v35, 0xba800000, v2
	v_fmac_f32_e32 v5, 0xba800000, v2
	v_fmac_f32_e32 v31, 0xba800000, v2
	v_fmac_f32_e32 v3, 0xba800000, v2
	v_fmac_f32_e32 v7, 0xba800000, v2
	v_mul_f32_e32 v2, v32, v32
	v_mul_f32_e32 v4, v34, v34
	v_pk_add_f32 v[44:45], v[88:89], v[44:45]
	v_pk_add_f32 v[42:43], v[42:43], v[48:49]
	v_pk_fma_f32 v[50:51], v[32:33], v[32:33], v[2:3] op_sel_hi:[1,1,0]
	v_pk_fma_f32 v[84:85], v[34:35], v[34:35], v[4:5] op_sel_hi:[1,1,0]
	v_pk_add_f32 v[44:45], v[44:45], v[44:45] op_sel_hi:[0,1]
	v_pk_add_f32 v[42:43], v[42:43], v[42:43] op_sel_hi:[0,1]
	v_mul_f32_e32 v50, v7, v7
	v_mul_f32_e32 v84, v3, v3
	v_mul_f32_e32 v44, v31, v31
	v_mul_f32_e32 v42, v5, v5
	v_pk_add_f32 v[46:47], v[50:51], v[84:85]
	v_pk_add_f32 v[42:43], v[44:45], v[42:43]
	s_nop 0
	v_pk_add_f32 v[42:43], v[46:47], v[42:43]
	s_nop 0
	v_add_f32_e32 v2, v42, v43
	v_mov_b32_e32 v4, v2
	s_nop 1
	v_add_f32_dpp v4, v4, v4 quad_perm:[1,0,3,2] row_mask:0xf bank_mask:0xf
	s_nop 1
	v_add_f32_dpp v4, v4, v4 quad_perm:[2,3,0,1] row_mask:0xf bank_mask:0xf
	s_nop 1
	v_add_f32_dpp v4, v4, v4 row_half_mirror row_mask:0xf bank_mask:0xf
	s_nop 1
	v_add_f32_dpp v4, v4, v4 row_mirror row_mask:0xf bank_mask:0xf
	s_nop 0
	v_readlane_b32 s44, v4, 0
	v_readlane_b32 s45, v4, 16
	v_readlane_b32 s46, v4, 32
	v_readlane_b32 s47, v4, 48
	s_nop 1
	v_mov_b32_e32 v4, s44
	v_add_f32_e32 v4, s45, v4
	v_add_f32_e32 v4, s46, v4
	v_add_f32_e32 v4, s47, v4
	v_or_b32_e32 v42, 1, v36
	v_ashrrev_i32_e32 v43, 31, v42
	v_lshlrev_b64 v[42:43], 11, v[42:43]
	v_lshl_add_u64 v[42:43], v[8:9], 0, v[42:43]
	global_load_dwordx2 v[44:45], v[42:43], off
	global_load_dwordx2 v[46:47], v[42:43], off offset:512
	global_load_dwordx2 v[50:51], v[42:43], off offset:1024
	global_load_dwordx2 v[48:49], v[42:43], off offset:1536
	s_add_i32 s46, s15, s3
	s_cmpk_lt_i32 s46, 0x400
	s_cselect_b32 s46, s46, s15
	s_lshl_b32 s45, s46, 4
	v_add_u32_e32 v108, s45, v56
	v_ashrrev_i32_e32 v109, 31, v108
	v_lshlrev_b64 v[108:109], 11, v[108:109]
	v_lshl_add_u64 v[108:109], v[8:9], 0, v[108:109]
	global_load_dwordx2 v[100:101], v[108:109], off
	global_load_dwordx2 v[102:103], v[108:109], off offset:512
	global_load_dwordx2 v[104:105], v[108:109], off offset:1024
	global_load_dwordx2 v[106:107], v[108:109], off offset:1536
	v_lshlrev_b64 v[36:37], 10, v[36:37]
	v_mov_b32_e32 v2, v4
	v_fmamk_f32 v2, v2, 0x3a800000, v71
	v_mul_f32_e32 v4, 0x4b800000, v2
	v_cmp_gt_f32_e32 vcc, s14, v2
	s_nop 1
	v_cndmask_b32_e32 v2, v2, v4, vcc
	v_rsq_f32_e32 v2, v2
	s_nop 0
	v_mul_f32_e32 v4, 0x45800000, v2
	v_cndmask_b32_e32 v6, v2, v4, vcc
	v_pk_mul_f32 v[40:41], v[40:41], v[6:7] op_sel_hi:[1,0]
	v_pk_mul_f32 v[42:43], v[82:83], v[6:7] op_sel_hi:[1,0]
	v_accvgpr_read_b32 v52, a8
	v_accvgpr_read_b32 v53, a9
	v_accvgpr_read_b32 v54, a10
	v_accvgpr_read_b32 v55, a11
	v_accvgpr_read_b32 v78, a12
	v_accvgpr_read_b32 v79, a13
	v_accvgpr_read_b32 v80, a14
	v_accvgpr_read_b32 v81, a15
	s_waitcnt vmcnt(8)
	v_pk_fma_f32 v[40:41], v[52:53], v[40:41], v[78:79]
	v_pk_fma_f32 v[82:83], v[54:55], v[42:43], v[80:81]
	v_cvt_pk_bf16_f32 v42, v40, v41
	v_mov_b32_e32 v2, 0
	v_cvt_pk_bf16_f32 v43, v82, v83
	global_store_dwordx2 v[0:1], v[42:43], off
	v_accvgpr_read_b32 v52, a16
	v_accvgpr_read_b32 v53, a17
	v_accvgpr_read_b32 v54, a18
	v_accvgpr_read_b32 v55, a19
	v_accvgpr_read_b32 v78, a20
	v_accvgpr_read_b32 v79, a21
	v_accvgpr_read_b32 v80, a22
	v_accvgpr_read_b32 v81, a23
	v_lshl_add_u64 v[42:43], v[28:29], 0, v[36:37]
	v_pk_mul_f32 v[32:33], v[32:33], v[6:7] op_sel_hi:[1,0]
	v_pk_mul_f32 v[34:35], v[34:35], v[6:7] op_sel_hi:[1,0]
	v_mov_b32_e32 v4, v31
	v_pk_mul_f32 v[4:5], v[4:5], v[6:7] op_sel_hi:[1,0]
	s_waitcnt vmcnt(5)
	v_and_b32_e32 v31, 0xffff0000, v48
	v_pk_add_f32 v[52:53], v[52:53], 1.0 op_sel_hi:[1,0]
	v_pk_add_f32 v[36:37], v[54:55], 1.0 op_sel_hi:[1,0]
	v_pk_fma_f32 v[52:53], v[52:53], v[40:41], v[78:79]
	v_pk_fma_f32 v[54:55], v[36:37], v[82:83], v[80:81]
	v_cvt_pk_fp8_f32 v2, v52, v53
	v_pk_mul_f32 v[36:37], v[38:39], v[6:7] op_sel_hi:[1,0]
	v_cvt_pk_fp8_f32 v2, v54, v55 op_sel:[0,0,1]
	global_store_dword v[42:43], v2, off
	v_accvgpr_read_b32 v78, a24
	v_accvgpr_read_b32 v79, a25
	v_accvgpr_read_b32 v80, a26
	v_accvgpr_read_b32 v81, a27
	v_accvgpr_read_b32 v82, a28
	v_accvgpr_read_b32 v83, a29
	v_accvgpr_read_b32 v84, a30
	v_accvgpr_read_b32 v85, a31
	v_pk_mul_f32 v[38:39], v[86:87], v[6:7] op_sel_hi:[1,0]
	ds_write_b128 v66, v[52:55]
	v_mov_b32_e32 v2, 0
	v_pk_fma_f32 v[40:41], v[80:81], v[38:39], v[84:85]
	v_pk_fma_f32 v[78:79], v[78:79], v[36:37], v[82:83]
	s_nop 0
	v_cvt_pk_bf16_f32 v36, v78, v79
	v_cvt_pk_bf16_f32 v37, v40, v41
	global_store_dwordx2 v[0:1], v[36:37], off offset:512
	v_accvgpr_read_b32 v36, a32
	v_accvgpr_read_b32 v37, a33
	v_accvgpr_read_b32 v38, a34
	v_accvgpr_read_b32 v39, a35
	s_nop 0
	v_accvgpr_read_b32 v52, a36
	v_accvgpr_read_b32 v53, a37
	v_accvgpr_read_b32 v54, a38
	v_accvgpr_read_b32 v55, a39
	v_pk_add_f32 v[36:37], v[36:37], 1.0 op_sel_hi:[1,0]
	v_pk_add_f32 v[38:39], v[38:39], 1.0 op_sel_hi:[1,0]
	v_pk_fma_f32 v[36:37], v[36:37], v[78:79], v[52:53]
	v_pk_fma_f32 v[38:39], v[38:39], v[40:41], v[54:55]
	v_cvt_pk_fp8_f32 v2, v36, v37
	s_nop 0
	v_cvt_pk_fp8_f32 v2, v38, v39 op_sel:[0,0,1]
	global_store_dword v[42:43], v2, off offset:256
	v_accvgpr_read_b32 v52, a40
	v_accvgpr_read_b32 v53, a41
	v_accvgpr_read_b32 v54, a42
	v_accvgpr_read_b32 v55, a43
	v_accvgpr_read_b32 v78, a44
	v_accvgpr_read_b32 v79, a45
	v_accvgpr_read_b32 v80, a46
	v_accvgpr_read_b32 v81, a47
	ds_write_b128 v66, v[36:39] offset:1024
	v_mov_b32_e32 v2, 0
	v_pk_fma_f32 v[40:41], v[34:35], v[54:55], v[80:81]
	v_pk_fma_f32 v[52:53], v[32:33], v[52:53], v[78:79]
	s_nop 0
	v_cvt_pk_bf16_f32 v32, v52, v53
	v_cvt_pk_bf16_f32 v33, v40, v41
	global_store_dwordx2 v[0:1], v[32:33], off offset:1024
	v_accvgpr_read_b32 v32, a48
	v_accvgpr_read_b32 v33, a49
	v_accvgpr_read_b32 v34, a50
	v_accvgpr_read_b32 v35, a51
	s_nop 0
	v_accvgpr_read_b32 v36, a52
	v_accvgpr_read_b32 v37, a53
	v_accvgpr_read_b32 v38, a54
	v_accvgpr_read_b32 v39, a55
	v_pk_add_f32 v[32:33], v[32:33], 1.0 op_sel_hi:[1,0]
	v_pk_add_f32 v[34:35], v[34:35], 1.0 op_sel_hi:[1,0]
	v_pk_fma_f32 v[32:33], v[52:53], v[32:33], v[36:37]
	v_pk_fma_f32 v[34:35], v[40:41], v[34:35], v[38:39]
	v_cvt_pk_fp8_f32 v2, v32, v33
	v_lshlrev_b32_e32 v38, 16, v50
	v_cvt_pk_fp8_f32 v2, v34, v35 op_sel:[0,0,1]
	global_store_dword v[42:43], v2, off offset:512
	v_accvgpr_read_b32 v78, a56
	v_accvgpr_read_b32 v79, a57
	v_accvgpr_read_b32 v80, a58
	v_accvgpr_read_b32 v81, a59
	v_accvgpr_read_b32 v82, a60
	v_accvgpr_read_b32 v83, a61
	v_accvgpr_read_b32 v84, a62
	v_accvgpr_read_b32 v85, a63
	v_mov_b32_e32 v2, v7
	v_pk_mul_f32 v[2:3], v[2:3], v[6:7] op_sel_hi:[1,0]
	ds_write_b128 v66, v[32:35] offset:2048
	v_and_b32_e32 v39, 0xffff0000, v50
	v_lshlrev_b32_e32 v40, 16, v51
	v_and_b32_e32 v41, 0xffff0000, v51
	v_lshlrev_b32_e32 v35, 16, v48
	v_lshlrev_b32_e32 v37, 16, v49
	v_and_b32_e32 v33, 0xffff0000, v49
	v_lshlrev_b32_e32 v49, 16, v45
	v_lshlrev_b32_e32 v48, 16, v44
	v_and_b32_e32 v51, 0xffff0000, v45
	v_and_b32_e32 v50, 0xffff0000, v44
	v_lshlrev_b32_e32 v45, 16, v47
	v_lshlrev_b32_e32 v44, 16, v46
	v_and_b32_e32 v47, 0xffff0000, v47
	v_and_b32_e32 v46, 0xffff0000, v46
	v_add_f32_e32 v36, v38, v39
	v_add_f32_e32 v32, v40, v41
	v_pk_fma_f32 v[52:53], v[4:5], v[80:81], v[84:85]
	v_pk_fma_f32 v[54:55], v[2:3], v[78:79], v[82:83]
	v_pk_add_f32 v[78:79], v[48:49], v[50:51]
	v_cvt_pk_bf16_f32 v2, v54, v55
	v_cvt_pk_bf16_f32 v3, v52, v53
	global_store_dwordx2 v[0:1], v[2:3], off offset:1536
	v_accvgpr_read_b32 v0, a64
	v_accvgpr_read_b32 v1, a65
	v_accvgpr_read_b32 v2, a66
	v_accvgpr_read_b32 v3, a67
	v_pk_add_f32 v[80:81], v[44:45], v[46:47]
	v_accvgpr_read_b32 v4, a68
	v_accvgpr_read_b32 v5, a69
	v_accvgpr_read_b32 v6, a70
	v_accvgpr_read_b32 v7, a71
	v_add_f32_e32 v30, v78, v79
	v_pk_add_f32 v[78:79], v[80:81], v[80:81] op_sel:[0,1] op_sel_hi:[1,0]
	v_add_f32_e32 v34, 0, v30
	v_mov_b32_e32 v79, v31
	v_pk_add_f32 v[80:81], v[36:37], v[32:33]
	v_pk_add_f32 v[78:79], v[34:35], v[78:79]
	v_mov_b32_e32 v34, 0
	v_pk_add_f32 v[78:79], v[78:79], v[80:81]
	v_pk_add_f32 v[0:1], v[0:1], 1.0 op_sel_hi:[1,0]
	v_add_f32_e32 v30, v78, v79
	ds_bpermute_b32 v32, v57, v30
	v_pk_add_f32 v[2:3], v[2:3], 1.0 op_sel_hi:[1,0]
	v_pk_fma_f32 v[78:79], v[54:55], v[0:1], v[4:5]
	v_pk_fma_f32 v[80:81], v[52:53], v[2:3], v[6:7]
	v_cvt_pk_fp8_f32 v34, v78, v79
	s_waitcnt lgkmcnt(0)
	v_add_f32_e32 v30, v30, v32
	ds_bpermute_b32 v32, v58, v30
	v_cvt_pk_fp8_f32 v34, v80, v81 op_sel:[0,0,1]
	global_store_dword v[42:43], v34, off offset:768
	v_accvgpr_read_b32 v52, a8
	v_accvgpr_read_b32 v53, a9
	v_accvgpr_read_b32 v54, a10
	v_accvgpr_read_b32 v55, a11
	v_accvgpr_read_b32 v82, a12
	v_accvgpr_read_b32 v83, a13
	v_accvgpr_read_b32 v84, a14
	v_accvgpr_read_b32 v85, a15
	ds_write_b128 v66, v[78:81] offset:3072
	s_waitcnt lgkmcnt(1)
	v_add_f32_e32 v30, v30, v32
	ds_bpermute_b32 v32, v59, v30
	s_waitcnt lgkmcnt(0)
	v_add_f32_e32 v30, v30, v32
	ds_bpermute_b32 v32, v60, v30
	s_waitcnt lgkmcnt(0)
	v_add_f32_e32 v30, v30, v32
	ds_bpermute_b32 v32, v61, v30
	s_waitcnt lgkmcnt(0)
	v_add_f32_e32 v30, v30, v32
	ds_bpermute_b32 v32, v62, v30
	s_waitcnt lgkmcnt(0)
	v_add_f32_e32 v30, v30, v32
	v_fmac_f32_e32 v50, 0xba800000, v30
	v_fmac_f32_e32 v51, 0xba800000, v30
	v_fmac_f32_e32 v49, 0xba800000, v30
	v_fmac_f32_e32 v46, 0xba800000, v30
	v_fmac_f32_e32 v47, 0xba800000, v30
	v_fmac_f32_e32 v45, 0xba800000, v30
	v_fmac_f32_e32 v48, 0xba800000, v30
	v_fmac_f32_e32 v44, 0xba800000, v30
	v_fmac_f32_e32 v38, 0xba800000, v30
	v_fmac_f32_e32 v40, 0xba800000, v30
	v_mov_b32_e32 v0, v49
	v_mov_b32_e32 v1, v51
	v_mov_b32_e32 v49, v50
	v_mov_b32_e32 v6, v45
	v_mov_b32_e32 v7, v47
	v_mov_b32_e32 v45, v46
	v_fmac_f32_e32 v39, 0xba800000, v30
	v_fmac_f32_e32 v41, 0xba800000, v30
	v_mul_f32_e32 v2, v38, v38
	v_mul_f32_e32 v4, v40, v40
	v_pk_mul_f32 v[42:43], v[0:1], v[0:1]
	v_pk_mul_f32 v[46:47], v[48:49], v[48:49]
	v_pk_mul_f32 v[50:51], v[6:7], v[6:7]
	v_pk_mul_f32 v[86:87], v[44:45], v[44:45]
	v_fmac_f32_e32 v31, 0xba800000, v30
	v_fmac_f32_e32 v35, 0xba800000, v30
	v_pk_fma_f32 v[2:3], v[38:39], v[38:39], v[2:3] op_sel_hi:[1,1,0]
	v_pk_fma_f32 v[4:5], v[40:41], v[40:41], v[4:5] op_sel_hi:[1,1,0]
	v_pk_mov_b32 v[88:89], v[46:47], v[42:43] op_sel:[1,0]
	v_mov_b32_e32 v47, v43
	v_pk_mov_b32 v[42:43], v[86:87], v[50:51] op_sel:[1,0]
	v_mov_b32_e32 v87, v51
	v_mul_f32_e32 v2, v35, v35
	v_mul_f32_e32 v4, v31, v31
	v_pk_add_f32 v[46:47], v[88:89], v[46:47]
	v_pk_add_f32 v[42:43], v[42:43], v[86:87]
	v_fmac_f32_e32 v33, 0xba800000, v30
	v_fmac_f32_e32 v37, 0xba800000, v30
	v_pk_add_f32 v[2:3], v[2:3], v[4:5]
	v_pk_add_f32 v[4:5], v[46:47], v[46:47] op_sel_hi:[0,1]
	v_pk_add_f32 v[42:43], v[42:43], v[42:43] op_sel_hi:[0,1]
	v_mul_f32_e32 v4, v37, v37
	v_mul_f32_e32 v42, v33, v33
	v_pk_add_f32 v[4:5], v[4:5], v[42:43]
	v_add_u32_e32 v42, s16, v67
	v_pk_add_f32 v[2:3], v[2:3], v[4:5]
	v_ashrrev_i32_e32 v43, 31, v42
	v_add_f32_e32 v2, v2, v3
	v_mov_b32_e32 v3, v2
	s_nop 1
	v_add_f32_dpp v3, v3, v3 quad_perm:[1,0,3,2] row_mask:0xf bank_mask:0xf
	s_nop 1
	v_add_f32_dpp v3, v3, v3 quad_perm:[2,3,0,1] row_mask:0xf bank_mask:0xf
	s_nop 1
	v_add_f32_dpp v3, v3, v3 row_half_mirror row_mask:0xf bank_mask:0xf
	s_nop 1
	v_add_f32_dpp v3, v3, v3 row_mirror row_mask:0xf bank_mask:0xf
	s_nop 0
	v_readlane_b32 s44, v3, 0
	v_readlane_b32 s45, v3, 16
	v_readlane_b32 s46, v3, 32
	v_readlane_b32 s47, v3, 48
	s_nop 1
	v_mov_b32_e32 v3, s44
	v_add_f32_e32 v3, s45, v3
	v_add_f32_e32 v3, s46, v3
	v_add_f32_e32 v3, s47, v3
	v_mov_b32_e32 v30, v35
	v_mov_b32_e32 v32, v37
	v_mov_b32_e32 v2, v3
	v_fmamk_f32 v2, v2, 0x3a800000, v71
	v_mul_f32_e32 v3, 0x4b800000, v2
	v_cmp_gt_f32_e32 vcc, s14, v2
	s_nop 1
	v_cndmask_b32_e32 v2, v2, v3, vcc
	v_rsq_f32_e32 v4, v2
	v_lshlrev_b64 v[2:3], 11, v[42:43]
	v_lshl_add_u64 v[2:3], v[8:9], 0, v[2:3]
	v_mul_f32_e32 v5, 0x45800000, v4
	v_cndmask_b32_e32 v4, v4, v5, vcc
	v_pk_mul_f32 v[46:47], v[48:49], v[4:5] op_sel_hi:[1,0]
	v_pk_mul_f32 v[0:1], v[0:1], v[4:5] op_sel_hi:[1,0]
	v_pk_fma_f32 v[78:79], v[52:53], v[46:47], v[82:83]
	v_pk_fma_f32 v[54:55], v[54:55], v[0:1], v[84:85]
	v_cvt_pk_bf16_f32 v0, v78, v79
	v_mov_b32_e32 v5, 0
	v_cvt_pk_bf16_f32 v1, v54, v55
	global_store_dwordx2 v[2:3], v[0:1], off
	v_accvgpr_read_b32 v46, a16
	v_accvgpr_read_b32 v47, a17
	v_accvgpr_read_b32 v48, a18
	v_accvgpr_read_b32 v49, a19
	v_accvgpr_read_b32 v50, a20
	v_accvgpr_read_b32 v51, a21
	v_accvgpr_read_b32 v52, a22
	v_accvgpr_read_b32 v53, a23
	v_lshlrev_b64 v[0:1], 10, v[42:43]
	v_lshl_add_u64 v[0:1], v[28:29], 0, v[0:1]
	v_pk_add_f32 v[46:47], v[46:47], 1.0 op_sel_hi:[1,0]
	v_pk_add_f32 v[42:43], v[48:49], 1.0 op_sel_hi:[1,0]
	v_pk_fma_f32 v[46:47], v[46:47], v[78:79], v[50:51]
	v_pk_fma_f32 v[48:49], v[42:43], v[54:55], v[52:53]
	v_cvt_pk_fp8_f32 v5, v46, v47
	s_nop 0
	v_cvt_pk_fp8_f32 v5, v48, v49 op_sel:[0,0,1]
	global_store_dword v[0:1], v5, off
	v_accvgpr_read_b32 v50, a24
	v_accvgpr_read_b32 v51, a25
	v_accvgpr_read_b32 v52, a26
	v_accvgpr_read_b32 v53, a27
	v_accvgpr_read_b32 v78, a28
	v_accvgpr_read_b32 v79, a29
	v_accvgpr_read_b32 v80, a30
	v_accvgpr_read_b32 v81, a31
	v_pk_mul_f32 v[42:43], v[44:45], v[4:5] op_sel_hi:[1,0]
	v_pk_mul_f32 v[6:7], v[6:7], v[4:5] op_sel_hi:[1,0]
	ds_write_b128 v68, v[46:49]
	v_mov_b32_e32 v5, 0
	v_pk_fma_f32 v[6:7], v[52:53], v[6:7], v[80:81]
	v_pk_fma_f32 v[50:51], v[50:51], v[42:43], v[78:79]
	s_nop 0
	v_cvt_pk_bf16_f32 v42, v50, v51
	v_cvt_pk_bf16_f32 v43, v6, v7
	global_store_dwordx2 v[2:3], v[42:43], off offset:512
	v_accvgpr_read_b32 v42, a32
	v_accvgpr_read_b32 v43, a33
	v_accvgpr_read_b32 v44, a34
	v_accvgpr_read_b32 v45, a35
	s_nop 0
	v_accvgpr_read_b32 v46, a36
	v_accvgpr_read_b32 v47, a37
	v_accvgpr_read_b32 v48, a38
	v_accvgpr_read_b32 v49, a39
	v_pk_add_f32 v[42:43], v[42:43], 1.0 op_sel_hi:[1,0]
	v_pk_add_f32 v[44:45], v[44:45], 1.0 op_sel_hi:[1,0]
	v_pk_fma_f32 v[42:43], v[42:43], v[50:51], v[46:47]
	v_pk_fma_f32 v[44:45], v[44:45], v[6:7], v[48:49]
	v_cvt_pk_fp8_f32 v5, v42, v43
	s_nop 0
	v_cvt_pk_fp8_f32 v5, v44, v45 op_sel:[0,0,1]
	global_store_dword v[0:1], v5, off offset:256
	v_accvgpr_read_b32 v46, a40
	v_accvgpr_read_b32 v47, a41
	v_accvgpr_read_b32 v48, a42
	v_accvgpr_read_b32 v49, a43
	v_accvgpr_read_b32 v50, a44
	v_accvgpr_read_b32 v51, a45
	v_accvgpr_read_b32 v52, a46
	v_accvgpr_read_b32 v53, a47
	v_pk_mul_f32 v[6:7], v[38:39], v[4:5] op_sel_hi:[1,0]
	v_pk_mul_f32 v[38:39], v[40:41], v[4:5] op_sel_hi:[1,0]
	ds_write_b128 v68, v[42:45] offset:1024
	v_mov_b32_e32 v5, 0
	v_pk_fma_f32 v[48:49], v[38:39], v[48:49], v[52:53]
	v_pk_fma_f32 v[6:7], v[6:7], v[46:47], v[50:51]
	s_nop 0
	v_cvt_pk_bf16_f32 v38, v6, v7
	v_cvt_pk_bf16_f32 v39, v48, v49
	global_store_dwordx2 v[2:3], v[38:39], off offset:1024
	v_accvgpr_read_b32 v38, a48
	v_accvgpr_read_b32 v39, a49
	v_accvgpr_read_b32 v40, a50
	v_accvgpr_read_b32 v41, a51
	s_nop 0
	v_accvgpr_read_b32 v42, a52
	v_accvgpr_read_b32 v43, a53
	v_accvgpr_read_b32 v44, a54
	v_accvgpr_read_b32 v45, a55
	v_pk_add_f32 v[38:39], v[38:39], 1.0 op_sel_hi:[1,0]
	v_pk_add_f32 v[40:41], v[40:41], 1.0 op_sel_hi:[1,0]
	v_pk_fma_f32 v[38:39], v[6:7], v[38:39], v[42:43]
	v_pk_fma_f32 v[40:41], v[48:49], v[40:41], v[44:45]
	v_cvt_pk_fp8_f32 v5, v38, v39
	s_nop 0
	v_cvt_pk_fp8_f32 v5, v40, v41 op_sel:[0,0,1]
	global_store_dword v[0:1], v5, off offset:512
	v_accvgpr_read_b32 v42, a56
	v_accvgpr_read_b32 v43, a57
	v_accvgpr_read_b32 v44, a58
	v_accvgpr_read_b32 v45, a59
	v_accvgpr_read_b32 v46, a60
	v_accvgpr_read_b32 v47, a61
	v_accvgpr_read_b32 v48, a62
	v_accvgpr_read_b32 v49, a63
	v_pk_mul_f32 v[6:7], v[30:31], v[4:5] op_sel_hi:[1,0]
	v_pk_mul_f32 v[4:5], v[32:33], v[4:5] op_sel_hi:[1,0]
	ds_write_b128 v68, v[38:41] offset:2048
	v_mov_b32_e32 v38, 0
	v_pk_fma_f32 v[34:35], v[4:5], v[44:45], v[48:49]
	v_pk_fma_f32 v[36:37], v[6:7], v[42:43], v[46:47]
	s_nop 0
	v_cvt_pk_bf16_f32 v4, v36, v37
	v_cvt_pk_bf16_f32 v5, v34, v35
	global_store_dwordx2 v[2:3], v[4:5], off offset:1536
	v_accvgpr_read_b32 v4, a64
	v_accvgpr_read_b32 v5, a65
	v_accvgpr_read_b32 v6, a66
	v_accvgpr_read_b32 v7, a67
	s_nop 0
	v_accvgpr_read_b32 v30, a68
	v_accvgpr_read_b32 v31, a69
	v_accvgpr_read_b32 v32, a70
	v_accvgpr_read_b32 v33, a71
	v_mov_b32_e32 v2, v70
	v_mov_b32_e32 v3, v69
	v_pk_add_f32 v[6:7], v[6:7], 1.0 op_sel_hi:[1,0]
	v_pk_add_f32 v[4:5], v[4:5], 1.0 op_sel_hi:[1,0]
	v_pk_fma_f32 v[6:7], v[34:35], v[6:7], v[32:33]
	v_pk_fma_f32 v[4:5], v[36:37], v[4:5], v[30:31]
	s_nop 0
	v_cvt_pk_fp8_f32 v38, v4, v5
	s_nop 0
	v_cvt_pk_fp8_f32 v38, v6, v7 op_sel:[0,0,1]
	ds_write_b128 v68, v[4:7] offset:3072
	global_store_dword v[0:1], v38, off offset:768
	s_waitcnt lgkmcnt(0)
	s_barrier
